# DIL unit loop: V loads kept in flight across K LDS write and S tiles (vmcnt 8 instead of 0)
# speedup vs baseline: 1.0001x; 1.0001x over previous
.LBB0_693:
	s_mov_b32 s34, s88
	s_add_i32 s88, s88, 1
	s_cmp_lt_i32 s88, s82
	s_cselect_b64 s[78:79], -1, 0
	s_mov_b64 s[98:99], s[78:79]
	s_and_b64 s[26:27], s[78:79], exec
	s_cselect_b32 s34, s88, s34
	s_and_b64 vcc, exec, s[6:7]
	s_mov_b64 s[26:27], -1
	s_cbranch_vccnz .LBB0_695
	s_mul_i32 s26, s34, s3
	s_add_i32 s42, s26, s2
	s_cbranch_execnz .LBB0_697
	s_branch .LBB0_696

.LBB0_710:
	s_add_i32 s27, s60, 8
	s_lshl_b32 s33, s31, 1
	s_and_b64 s[30:31], exec, s[64:65]
	s_cselect_b32 s27, s27, s33
	v_mad_i32_i24 v50, s61, v155, v74
	s_lshl_b32 s30, s61, 5
	v_add_u32_e32 v59, s30, v50
	v_and_b32_e32 v66, s26, v166
	v_and_b32_e32 v67, s26, v167
	v_and_b32_e32 v77, s26, v168
	v_med3_i32 v51, v50, 0, v187
	v_lshl_or_b32 v75, s62, 24, v164
	v_med3_i32 v50, v59, 0, v187
	v_add_u32_e32 v59, s30, v59
	v_mad_i32_i24 v66, v66, s61, v74
	s_add_i32 s30, s27, s68
	v_mad_i32_i24 v67, v67, s61, v74
	v_mad_i32_i24 v77, v77, s61, v74
	v_med3_i32 v66, v66, 0, v187
	v_lshl_add_u32 v76, s30, 8, v75
	v_med3_i32 v67, v67, 0, v187
	v_med3_i32 v77, v77, 0, v187
	v_and_b32_e32 v60, s26, v165
	v_lshl_add_u32 v66, v66, 12, v76
	v_lshl_add_u32 v70, v67, 12, v76
	v_lshl_add_u32 v76, v77, 12, v76
	v_and_b32_e32 v77, s26, v169
	v_mad_i32_i24 v60, v60, s61, v74
	v_mad_i32_i24 v74, v77, s61, v74
	v_med3_i32 v74, v74, 0, v187
	v_and_b32_e64 v77, s68, 1
	v_lshl_add_u32 v58, s27, 8, v75
	v_med3_i32 v59, v59, 0, v187
	v_med3_i32 v60, v60, 0, v187
	v_lshlrev_b32_e32 v74, 12, v74
	v_add_lshl_u32 v77, s27, v77, 8
	v_lshl_add_u32 v51, v51, 12, v58
	v_lshl_add_u32 v54, v50, 12, v58
	v_lshl_add_u32 v59, v59, 12, v58
	v_lshl_add_u32 v62, v60, 12, v58
	v_add3_u32 v78, v77, v75, v74
	global_load_dwordx4 v[50:53], v51, s[54:55]
	s_nop 0
	global_load_dwordx4 v[54:57], v54, s[54:55]
	s_nop 0
	global_load_dwordx4 v[58:61], v59, s[54:55]
	s_nop 0
	global_load_dwordx4 v[62:65], v62, s[54:55]
	s_nop 0
	global_load_dwordx4 v[66:69], v66, s[54:55]
	s_nop 0
	global_load_dwordx4 v[70:73], v70, s[54:55]
	s_nop 0
	global_load_dwordx4 v[74:77], v76, s[54:55]
	s_nop 0
	global_load_dwordx4 v[78:81], v78, s[54:55]
	v_add_u32_e32 v82, v173, v177
	s_waitcnt vmcnt(8)
	ds_write_b128 v82, v[2:5]
	ds_write_b128 v82, v[6:9] offset:8704
	ds_write_b128 v82, v[10:13] offset:17408
	ds_write_b128 v82, v[14:17] offset:26112
	ds_write_b128 v82, v[18:21] offset:34816
	ds_write_b128 v82, v[22:25] offset:43520
	ds_write_b128 v82, v[26:29] offset:52224
	ds_write_b128 v82, v[30:33] offset:60928
	s_and_saveexec_b64 s[26:27], s[0:1]
	s_cbranch_execz .LBB0_712
	v_pk_add_f32 v[82:83], v[160:161], v[158:159]
	s_nop 0
	v_add_f32_e32 v82, v82, v83
	v_fmamk_f32 v82, v82, 0x3c000000, v186
	v_rsq_f32_e32 v82, v82
	ds_write_b32 v176, v82

.LBB0_724:
	v_add_f32_e32 v156, v163, v190
	v_add_f32_e32 v163, v191, v192
	v_add_f32_e32 v156, v156, v163
	v_fmamk_f32 v156, v156, 0x3c000000, v186
	s_add_i32 s26, s96, -1
	v_rsq_f32_e32 v156, v156
	s_cmp_lg_u32 s84, 0
	s_cselect_b64 s[74:75], -1, 0
	s_cmp_eq_u32 s84, s26
	s_movk_i32 s26, 0xc0
	s_cselect_b32 s26, s26, 0x100
	s_cmpk_gt_u32 s97, 0xff
	s_cselect_b64 s[76:77], -1, 0
	v_mul_f32_e32 v156, 0x3e0293ee, v156
	s_or_b64 s[76:77], s[74:75], s[76:77]
	v_cmp_gt_u32_e32 vcc, s26, v197
	v_mul_f32_e32 v82, v156, v82
	s_and_b64 vcc, s[76:77], vcc
	v_mul_f32_e32 v82, v86, v82
	s_and_b64 vcc, vcc, s[8:9]
	v_cndmask_b32_e32 v86, v188, v82, vcc
	v_mul_f32_e32 v82, v156, v83
	v_or_b32_e32 v83, 1, v197
	v_cmp_gt_u32_e32 vcc, s26, v83
	s_and_b64 vcc, s[76:77], vcc
	v_mul_f32_e32 v82, v87, v82
	s_and_b64 vcc, vcc, s[10:11]
	v_mul_f32_e32 v83, v156, v84
	v_or_b32_e32 v84, 2, v197
	v_cndmask_b32_e32 v163, v188, v82, vcc
	v_cmp_gt_u32_e32 vcc, s26, v84
	s_and_b64 vcc, s[76:77], vcc
	v_mul_f32_e32 v83, v88, v83
	s_and_b64 vcc, vcc, s[12:13]
	v_or_b32_e32 v84, 3, v197
	v_cndmask_b32_e32 v88, v188, v83, vcc
	v_cmp_gt_u32_e32 vcc, s26, v84
	s_and_b64 s[76:77], s[76:77], vcc
	s_and_b64 vcc, s[76:77], s[14:15]
	v_mul_f32_e32 v83, v156, v85
	s_cmpk_gt_u32 s97, 0xbf
	v_mul_f32_e32 v83, v89, v83
	s_cselect_b64 s[76:77], -1, 0
	v_cndmask_b32_e32 v89, v188, v83, vcc
	v_mul_f32_e32 v83, v156, v90
	s_or_b64 s[76:77], s[74:75], s[76:77]
	v_cmp_gt_u32_e32 vcc, s26, v198
	s_waitcnt lgkmcnt(7)
	v_mul_f32_e32 v83, v94, v83
	s_and_b64 vcc, s[76:77], vcc
	v_or_b32_e32 v84, 1, v198
	v_cndmask_b32_e32 v90, v188, v83, vcc
	v_mul_f32_e32 v83, v156, v91
	v_cmp_gt_u32_e32 vcc, s26, v84
	v_mul_f32_e32 v83, v95, v83
	s_and_b64 vcc, s[76:77], vcc
	v_or_b32_e32 v84, 2, v198
	v_cndmask_b32_e32 v91, v188, v83, vcc
	v_mul_f32_e32 v83, v156, v92
	v_cmp_gt_u32_e32 vcc, s26, v84
	v_mul_f32_e32 v83, v96, v83
	s_and_b64 vcc, s[76:77], vcc
	v_or_b32_e32 v84, 3, v198
	v_cndmask_b32_e32 v92, v188, v83, vcc
	v_cmp_gt_u32_e32 vcc, s26, v84
	s_and_b64 vcc, s[76:77], vcc
	v_mul_f32_e32 v83, v156, v93
	s_cmpk_gt_u32 s97, 0x7f
	v_mul_f32_e32 v83, v97, v83
	s_cselect_b64 s[76:77], -1, 0
	v_cndmask_b32_e32 v93, v188, v83, vcc
	v_mul_f32_e32 v83, v156, v98
	s_or_b64 s[76:77], s[74:75], s[76:77]
	v_cmp_gt_u32_e32 vcc, s26, v199
	s_waitcnt lgkmcnt(6)
	v_mul_f32_e32 v83, v102, v83
	s_and_b64 vcc, s[76:77], vcc
	v_or_b32_e32 v84, 1, v199
	v_cndmask_b32_e32 v94, v188, v83, vcc
	v_mul_f32_e32 v83, v156, v99
	v_cmp_gt_u32_e32 vcc, s26, v84
	v_mul_f32_e32 v83, v103, v83
	s_and_b64 vcc, s[76:77], vcc
	v_or_b32_e32 v84, 2, v199
	v_cndmask_b32_e32 v95, v188, v83, vcc
	v_mul_f32_e32 v83, v156, v100
	v_cmp_gt_u32_e32 vcc, s26, v84
	v_mul_f32_e32 v83, v104, v83
	s_and_b64 vcc, s[76:77], vcc
	v_or_b32_e32 v84, 3, v199
	v_cndmask_b32_e32 v96, v188, v83, vcc
	v_cmp_gt_u32_e32 vcc, s26, v84
	s_and_b64 vcc, s[76:77], vcc
	v_mul_f32_e32 v83, v156, v101
	s_cmp_gt_u32 s97, 63
	v_mul_f32_e32 v83, v105, v83
	s_cselect_b64 s[76:77], -1, 0
	v_cndmask_b32_e32 v97, v188, v83, vcc
	v_mul_f32_e32 v83, v156, v106
	s_or_b64 s[74:75], s[74:75], s[76:77]
	v_cmp_gt_u32_e32 vcc, s26, v200
	s_waitcnt lgkmcnt(5)
	v_mul_f32_e32 v83, v110, v83
	s_and_b64 vcc, s[74:75], vcc
	v_or_b32_e32 v84, 1, v200
	v_cndmask_b32_e32 v98, v188, v83, vcc
	v_mul_f32_e32 v83, v156, v107
	v_cmp_gt_u32_e32 vcc, s26, v84
	v_mul_f32_e32 v83, v111, v83
	s_and_b64 vcc, s[74:75], vcc
	v_or_b32_e32 v84, 2, v200
	v_cndmask_b32_e32 v99, v188, v83, vcc
	v_mul_f32_e32 v83, v156, v108
	v_cmp_gt_u32_e32 vcc, s26, v84
	v_mul_f32_e32 v83, v112, v83
	s_and_b64 vcc, s[74:75], vcc
	v_or_b32_e32 v84, 3, v200
	v_cndmask_b32_e32 v100, v188, v83, vcc
	v_mul_f32_e32 v83, v156, v109
	v_cmp_gt_u32_e32 vcc, s26, v84
	v_mul_f32_e32 v83, v113, v83
	s_and_b64 vcc, s[74:75], vcc
	v_cndmask_b32_e32 v101, v188, v83, vcc
	v_mul_f32_e32 v83, v156, v114
	s_waitcnt lgkmcnt(4)
	v_mul_f32_e32 v83, v118, v83
	v_cmp_gt_u32_e32 vcc, s26, v201
	v_or_b32_e32 v84, 1, v201
	v_max3_f32 v82, v86, s87, v163
	v_cndmask_b32_e32 v102, v188, v83, vcc
	v_mul_f32_e32 v83, v156, v115
	v_mul_f32_e32 v83, v119, v83
	v_cmp_gt_u32_e32 vcc, s26, v84
	v_or_b32_e32 v84, 2, v201
	v_max3_f32 v82, v82, v88, v89
	v_cndmask_b32_e32 v103, v188, v83, vcc
	v_mul_f32_e32 v83, v156, v116
	v_mul_f32_e32 v83, v120, v83
	v_cmp_gt_u32_e32 vcc, s26, v84
	v_or_b32_e32 v84, 3, v201
	v_max3_f32 v82, v82, v90, v91
	v_cndmask_b32_e32 v104, v188, v83, vcc
	v_mul_f32_e32 v83, v156, v117
	v_mul_f32_e32 v83, v121, v83
	v_cmp_gt_u32_e32 vcc, s26, v84
	v_or_b32_e32 v84, 1, v202
	v_max3_f32 v82, v82, v92, v93
	v_cndmask_b32_e32 v105, v188, v83, vcc
	v_mul_f32_e32 v83, v156, v122
	s_waitcnt lgkmcnt(3)
	v_mul_f32_e32 v83, v126, v83
	v_cmp_gt_u32_e32 vcc, s26, v202
	v_max3_f32 v82, v82, v94, v95
	v_max3_f32 v82, v82, v96, v97
	v_cndmask_b32_e32 v106, v188, v83, vcc
	v_mul_f32_e32 v83, v156, v123
	v_mul_f32_e32 v83, v127, v83
	v_cmp_gt_u32_e32 vcc, s26, v84
	v_or_b32_e32 v84, 2, v202
	v_max3_f32 v82, v82, v98, v99
	v_cndmask_b32_e32 v108, v188, v83, vcc
	v_mul_f32_e32 v83, v156, v124
	v_mul_f32_e32 v83, v128, v83
	v_cmp_gt_u32_e32 vcc, s26, v84
	v_or_b32_e32 v84, 3, v202
	v_max3_f32 v82, v82, v100, v101
	v_cndmask_b32_e32 v109, v188, v83, vcc
	v_mul_f32_e32 v83, v156, v125
	v_mul_f32_e32 v83, v129, v83
	v_cmp_gt_u32_e32 vcc, s26, v84
	v_or_b32_e32 v84, 1, v203
	v_max3_f32 v82, v82, v102, v103
	v_cndmask_b32_e32 v110, v188, v83, vcc
	v_mul_f32_e32 v83, v156, v130
	s_waitcnt lgkmcnt(2)
	v_mul_f32_e32 v83, v134, v83
	v_cmp_gt_u32_e32 vcc, s26, v203
	v_max3_f32 v82, v82, v104, v105
	v_max3_f32 v82, v82, v106, v108
	v_cndmask_b32_e32 v111, v188, v83, vcc
	v_mul_f32_e32 v83, v156, v131
	v_mul_f32_e32 v83, v135, v83
	v_cmp_gt_u32_e32 vcc, s26, v84
	v_or_b32_e32 v84, 2, v203
	v_max3_f32 v82, v82, v109, v110
	v_cndmask_b32_e32 v112, v188, v83, vcc
	v_mul_f32_e32 v83, v156, v132
	v_mul_f32_e32 v83, v136, v83
	v_cmp_gt_u32_e32 vcc, s26, v84
	v_or_b32_e32 v84, 3, v203
	v_max3_f32 v82, v82, v111, v112
	v_cndmask_b32_e32 v113, v188, v83, vcc
	v_mul_f32_e32 v83, v156, v133
	v_mul_f32_e32 v83, v137, v83
	v_cmp_gt_u32_e32 vcc, s26, v84
	v_or_b32_e32 v84, 1, v204
	v_or_b32_e32 v107, 3, v205
	v_cndmask_b32_e32 v114, v188, v83, vcc
	v_mul_f32_e32 v83, v156, v138
	s_waitcnt lgkmcnt(1)
	v_mul_f32_e32 v83, v142, v83
	v_cmp_gt_u32_e32 vcc, s26, v204
	v_max3_f32 v82, v82, v113, v114
	v_add_u32_e32 v121, v174, v177
	v_cndmask_b32_e32 v115, v188, v83, vcc
	v_mul_f32_e32 v83, v156, v139
	v_mul_f32_e32 v83, v143, v83
	v_cmp_gt_u32_e32 vcc, s26, v84
	v_or_b32_e32 v84, 2, v204
	s_cmp_lg_u64 s[98:99], 0
	s_cbranch_scc0 .Lmy_dil_vw_all
	s_waitcnt vmcnt(20)
	s_branch .Lmy_dil_vw_done

.Lmy_dil_vw_done:
	ds_write_b128 v121, v[50:53]
	ds_write_b128 v121, v[54:57] offset:8704
	ds_write_b128 v121, v[58:61] offset:17408
	ds_write_b128 v121, v[62:65] offset:26112
	ds_write_b128 v121, v[66:69] offset:34816
	ds_write_b128 v121, v[70:73] offset:43520
	ds_write_b128 v121, v[74:77] offset:52224
	ds_write_b128 v121, v[78:81] offset:60928
	v_cndmask_b32_e32 v116, v188, v83, vcc
	v_mul_f32_e32 v83, v156, v140
	v_mul_f32_e32 v83, v144, v83
	v_cmp_gt_u32_e32 vcc, s26, v84
	v_or_b32_e32 v84, 3, v204
	v_max3_f32 v82, v82, v115, v116
	v_cndmask_b32_e32 v117, v188, v83, vcc
	v_mul_f32_e32 v83, v156, v141
	v_mul_f32_e32 v83, v145, v83
	v_cmp_gt_u32_e32 vcc, s26, v84
	v_or_b32_e32 v84, 1, v205
	s_waitcnt lgkmcnt(0)
	v_cndmask_b32_e32 v118, v188, v83, vcc
	v_mul_f32_e32 v83, v156, v146
	v_cmp_gt_u32_e32 vcc, s26, v205
	v_mul_f32_e32 v83, v150, v83
	s_and_b64 vcc, vcc, s[16:17]
	v_cndmask_b32_e32 v87, v188, v83, vcc
	v_mul_f32_e32 v83, v156, v147
	v_cmp_gt_u32_e32 vcc, s26, v84
	v_mul_f32_e32 v83, v151, v83
	s_and_b64 vcc, vcc, s[18:19]
	v_or_b32_e32 v84, 2, v205
	v_cndmask_b32_e32 v85, v188, v83, vcc
	v_mul_f32_e32 v83, v156, v148
	v_cmp_gt_u32_e32 vcc, s26, v84
	v_mul_f32_e32 v83, v152, v83
	s_and_b64 vcc, vcc, s[20:21]
	v_cndmask_b32_e32 v83, v188, v83, vcc
	v_mul_f32_e32 v84, v156, v149
	v_cmp_gt_u32_e32 vcc, s26, v107
	v_max3_f32 v82, v82, v117, v118
	v_mul_f32_e32 v84, v153, v84
	s_and_b64 vcc, vcc, s[22:23]
	v_max3_f32 v82, v82, v87, v85
	v_cndmask_b32_e32 v84, v188, v84, vcc
	v_max3_f32 v82, v82, v83, v84
	ds_bpermute_b32 v107, v184, v82
	s_and_b64 s[26:27], exec, s[64:65]
	s_cselect_b32 s26, 7, 3
	s_min_u32 s27, s78, 0xf0
	s_min_u32 s31, s79, 0xf0
	s_waitcnt lgkmcnt(0)
	v_max_f32_e32 v107, v107, v107
	v_max_f32_e32 v82, v82, v107
	ds_bpermute_b32 v107, v185, v82
	v_or_b32_e32 v52, s27, v179
	v_mad_u32_u24 v80, v52, s86, v175
	v_or_b32_e32 v52, s31, v179
	s_barrier
	s_waitcnt lgkmcnt(0)
	v_max3_f32 v82, v82, v107, s87
	v_sub_f32_e32 v86, v86, v82
	v_exp_f32_e32 v107, v86
	v_sub_f32_e32 v120, v163, v82
	v_exp_f32_e32 v120, v120
	v_sub_f32_e32 v88, v88, v82
	v_exp_f32_e32 v88, v88
	v_sub_f32_e32 v89, v89, v82
	v_exp_f32_e32 v89, v89
	v_sub_f32_e32 v90, v90, v82
	v_add_f32_e32 v119, 0, v107
	v_exp_f32_e32 v90, v90
	v_sub_f32_e32 v91, v91, v82
	v_add_f32_e32 v119, v120, v119
	v_exp_f32_e32 v91, v91
	v_sub_f32_e32 v92, v92, v82
	v_add_f32_e32 v119, v88, v119
	v_exp_f32_e32 v92, v92
	v_sub_f32_e32 v93, v93, v82
	v_add_f32_e32 v119, v89, v119
	v_exp_f32_e32 v93, v93
	v_sub_f32_e32 v94, v94, v82
	v_add_f32_e32 v119, v90, v119
	v_exp_f32_e32 v94, v94
	v_sub_f32_e32 v95, v95, v82
	v_add_f32_e32 v119, v91, v119
	v_exp_f32_e32 v95, v95
	v_sub_f32_e32 v96, v96, v82
	v_add_f32_e32 v119, v92, v119
	v_exp_f32_e32 v96, v96
	v_sub_f32_e32 v97, v97, v82
	v_add_f32_e32 v119, v93, v119
	v_exp_f32_e32 v97, v97
	v_sub_f32_e32 v98, v98, v82
	v_add_f32_e32 v119, v94, v119
	v_exp_f32_e32 v98, v98
	v_sub_f32_e32 v99, v99, v82
	v_add_f32_e32 v119, v95, v119
	v_exp_f32_e32 v99, v99
	v_sub_f32_e32 v100, v100, v82
	v_add_f32_e32 v119, v96, v119
	v_exp_f32_e32 v100, v100
	v_add_f32_e32 v119, v97, v119
	v_add_f32_e32 v119, v98, v119
	v_add_f32_e32 v70, v99, v119
	v_cvt_pk_bf16_f32 v53, v92, v93
	v_add_f32_e32 v92, v100, v70
	v_sub_f32_e32 v70, v101, v82
	v_cvt_pk_bf16_f32 v50, v107, v120
	v_mad_u32_u24 v107, v52, s86, v175
	v_exp_f32_e32 v101, v70
	v_sub_f32_e32 v70, v102, v82
	v_cvt_pk_bf16_f32 v51, v88, v89
	ds_read_b64_tr_b16 v[56:57], v107
	ds_read_b64_tr_b16 v[54:55], v80
	v_cvt_pk_bf16_f32 v52, v90, v91
	ds_read_b64_tr_b16 v[60:61], v107 offset:32
	ds_read_b64_tr_b16 v[58:59], v80 offset:32
	ds_read_b64_tr_b16 v[62:63], v80 offset:64
	ds_read_b64_tr_b16 v[66:67], v80 offset:96
	ds_read_b64_tr_b16 v[64:65], v107 offset:64
	ds_read_b64_tr_b16 v[68:69], v107 offset:96
	v_exp_f32_e32 v119, v70
	ds_read_b64_tr_b16 v[70:71], v80 offset:128
	ds_read_b64_tr_b16 v[72:73], v107 offset:128
	ds_read_b64_tr_b16 v[76:77], v107 offset:160
	ds_read_b64_tr_b16 v[74:75], v80 offset:160
	ds_read_b64_tr_b16 v[78:79], v80 offset:192
	ds_read_b64_tr_b16 v[88:89], v80 offset:224
	ds_read_b64_tr_b16 v[80:81], v107 offset:192
	ds_read_b64_tr_b16 v[90:91], v107 offset:224
	v_sub_f32_e32 v93, v103, v82
	v_exp_f32_e32 v120, v93
	v_add_f32_e32 v92, v101, v92
	s_min_u32 s27, s78, 0xd0
	s_waitcnt lgkmcnt(14)
	v_mfma_f32_16x16x32_bf16 v[54:57], v[54:57], v[50:53], 0
	v_add_f32_e32 v92, v119, v92
	s_min_u32 s31, s42, 0xf0
	v_add_f32_e32 v121, v120, v92
	s_waitcnt lgkmcnt(12)
	v_mfma_f32_16x16x32_bf16 v[58:61], v[58:61], v[50:53], 0
	v_sub_f32_e32 v92, v104, v82
	v_exp_f32_e32 v122, v92
	v_sub_f32_e32 v92, v105, v82
	s_waitcnt lgkmcnt(9)
	v_mfma_f32_16x16x32_bf16 v[62:65], v[62:65], v[50:53], 0
	v_exp_f32_e32 v123, v92
	v_sub_f32_e32 v124, v106, v82
	v_exp_f32_e32 v124, v124
	s_waitcnt lgkmcnt(8)
	v_mfma_f32_16x16x32_bf16 v[66:69], v[66:69], v[50:53], 0
	v_sub_f32_e32 v109, v109, v82
	v_exp_f32_e32 v109, v109
	v_sub_f32_e32 v112, v112, v82
	s_waitcnt lgkmcnt(6)
	v_mfma_f32_16x16x32_bf16 v[70:73], v[70:73], v[50:53], 0
	s_min_u32 s30, s30, 0xf0
	v_sub_f32_e32 v87, v87, v82
	v_sub_f32_e32 v85, v85, v82
	s_waitcnt lgkmcnt(4)
	v_mfma_f32_16x16x32_bf16 v[74:77], v[74:77], v[50:53], 0
	v_sub_f32_e32 v86, 0xf149f2ca, v82
	v_sub_f32_e32 v84, v84, v82
	v_sub_f32_e32 v83, v83, v82
	s_waitcnt lgkmcnt(1)
	v_mfma_f32_16x16x32_bf16 v[78:81], v[78:81], v[50:53], 0
	v_exp_f32_e32 v83, v83
	s_and_b32 s26, s33, s26
	v_mov_b32_e32 v163, v157
	s_waitcnt lgkmcnt(0)
	v_mfma_f32_16x16x32_bf16 v[50:53], v[88:91], v[50:53], 0
	v_add_u32_e32 v90, s27, v180
	v_mad_u32_u24 v125, v90, s86, v175
	v_or_b32_e32 v90, s31, v179
	v_mad_u32_u24 v126, v90, s86, v175
	v_cvt_pk_bf16_f32 v88, v94, v95
	ds_read_b64_tr_b16 v[94:95], v126
	ds_read_b64_tr_b16 v[92:93], v125
	v_cvt_pk_bf16_f32 v89, v96, v97
	v_cvt_pk_bf16_f32 v90, v98, v99
	v_cvt_pk_bf16_f32 v91, v100, v101
	ds_read_b64_tr_b16 v[98:99], v126 offset:32
	ds_read_b64_tr_b16 v[96:97], v125 offset:32
	ds_read_b64_tr_b16 v[100:101], v125 offset:64
	ds_read_b64_tr_b16 v[104:105], v125 offset:96
	ds_read_b64_tr_b16 v[102:103], v126 offset:64
	ds_read_b64_tr_b16 v[106:107], v126 offset:96
	s_waitcnt lgkmcnt(6)
	v_mfma_f32_16x16x32_bf16 v[54:57], v[92:95], v[88:91], v[54:57]
	v_add_f32_e32 v92, v122, v121
	v_add_f32_e32 v92, v123, v92
	v_add_f32_e32 v121, v124, v92
	v_sub_f32_e32 v92, v108, v82
	v_exp_f32_e32 v108, v92
	ds_read_b64_tr_b16 v[92:93], v125 offset:128
	ds_read_b64_tr_b16 v[94:95], v126 offset:128
	s_waitcnt lgkmcnt(6)
	v_mfma_f32_16x16x32_bf16 v[58:61], v[96:99], v[88:91], v[58:61]
	s_min_u32 s27, s78, 0xb0
	s_min_u32 s31, s43, 0xf0
	s_waitcnt lgkmcnt(3)
	v_mfma_f32_16x16x32_bf16 v[62:65], v[100:103], v[88:91], v[62:65]
	s_waitcnt lgkmcnt(2)
	v_mfma_f32_16x16x32_bf16 v[66:69], v[104:107], v[88:91], v[66:69]
	ds_read_b64_tr_b16 v[98:99], v126 offset:160
	ds_read_b64_tr_b16 v[96:97], v125 offset:160
	ds_read_b64_tr_b16 v[100:101], v125 offset:192
	ds_read_b64_tr_b16 v[104:105], v125 offset:224
	ds_read_b64_tr_b16 v[102:103], v126 offset:192
	ds_read_b64_tr_b16 v[106:107], v126 offset:224
	s_waitcnt lgkmcnt(6)
	v_mfma_f32_16x16x32_bf16 v[70:73], v[92:95], v[88:91], v[70:73]
	v_sub_f32_e32 v92, v110, v82
	v_exp_f32_e32 v110, v92
	v_add_f32_e32 v92, v108, v121
	s_waitcnt lgkmcnt(4)
	v_mfma_f32_16x16x32_bf16 v[74:77], v[96:99], v[88:91], v[74:77]
	v_add_f32_e32 v92, v109, v92
	v_add_f32_e32 v121, v110, v92
	v_sub_f32_e32 v92, v111, v82
	s_waitcnt lgkmcnt(1)
	v_mfma_f32_16x16x32_bf16 v[78:81], v[100:103], v[88:91], v[78:81]
	v_exp_f32_e32 v111, v92
	s_waitcnt lgkmcnt(0)
	v_mfma_f32_16x16x32_bf16 v[50:53], v[104:107], v[88:91], v[50:53]
	v_add_u32_e32 v90, s27, v181
	v_cvt_pk_bf16_f32 v88, v119, v120
	v_mad_u32_u24 v119, v90, s86, v175
	v_or_b32_e32 v90, s31, v179
	v_mad_u32_u24 v120, v90, s86, v175
	ds_read_b64_tr_b16 v[94:95], v120
	ds_read_b64_tr_b16 v[92:93], v119
	v_cvt_pk_bf16_f32 v89, v122, v123
	v_cvt_pk_bf16_f32 v90, v124, v108
	v_cvt_pk_bf16_f32 v91, v109, v110
	v_exp_f32_e32 v108, v112
	ds_read_b64_tr_b16 v[98:99], v120 offset:32
	ds_read_b64_tr_b16 v[96:97], v119 offset:32
	ds_read_b64_tr_b16 v[100:101], v119 offset:64
	ds_read_b64_tr_b16 v[104:105], v119 offset:96
	ds_read_b64_tr_b16 v[102:103], v120 offset:64
	ds_read_b64_tr_b16 v[106:107], v120 offset:96
	s_waitcnt lgkmcnt(6)
	v_mfma_f32_16x16x32_bf16 v[54:57], v[92:95], v[88:91], v[54:57]
	v_sub_f32_e32 v92, v113, v82
	v_exp_f32_e32 v109, v92
	v_add_f32_e32 v92, v111, v121
	v_add_f32_e32 v92, v108, v92
	s_waitcnt lgkmcnt(4)
	v_mfma_f32_16x16x32_bf16 v[58:61], v[96:99], v[88:91], v[58:61]
	v_add_f32_e32 v110, v109, v92
	ds_read_b64_tr_b16 v[92:93], v119 offset:128
	ds_read_b64_tr_b16 v[94:95], v120 offset:128
	v_sub_f32_e32 v112, v114, v82
	s_waitcnt lgkmcnt(3)
	v_mfma_f32_16x16x32_bf16 v[62:65], v[100:103], v[88:91], v[62:65]
	v_exp_f32_e32 v112, v112
	s_min_u32 s27, s78, 0x90
	s_waitcnt lgkmcnt(2)
	v_mfma_f32_16x16x32_bf16 v[66:69], v[104:107], v[88:91], v[66:69]
	ds_read_b64_tr_b16 v[98:99], v120 offset:160
	ds_read_b64_tr_b16 v[96:97], v119 offset:160
	ds_read_b64_tr_b16 v[100:101], v119 offset:192
	ds_read_b64_tr_b16 v[104:105], v119 offset:224
	ds_read_b64_tr_b16 v[102:103], v120 offset:192
	ds_read_b64_tr_b16 v[106:107], v120 offset:224
	s_waitcnt lgkmcnt(6)
	v_mfma_f32_16x16x32_bf16 v[70:73], v[92:95], v[88:91], v[70:73]
	v_sub_f32_e32 v92, v115, v82
	v_exp_f32_e32 v113, v92
	v_sub_f32_e32 v92, v116, v82
	s_waitcnt lgkmcnt(4)
	v_mfma_f32_16x16x32_bf16 v[74:77], v[96:99], v[88:91], v[74:77]
	v_exp_f32_e32 v114, v92
	v_sub_f32_e32 v92, v117, v82
	v_exp_f32_e32 v115, v92
	s_waitcnt lgkmcnt(1)
	v_mfma_f32_16x16x32_bf16 v[78:81], v[100:103], v[88:91], v[78:81]
	v_sub_f32_e32 v92, v118, v82
	v_exp_f32_e32 v116, v92
	s_waitcnt lgkmcnt(0)
	v_mfma_f32_16x16x32_bf16 v[50:53], v[104:107], v[88:91], v[50:53]
	v_add_u32_e32 v90, s27, v182
	v_cvt_pk_bf16_f32 v88, v111, v108
	v_mad_u32_u24 v108, v90, s86, v175
	v_or_b32_e32 v90, s30, v179
	v_cvt_pk_bf16_f32 v89, v109, v112
	v_mad_u32_u24 v109, v90, s86, v175
	ds_read_b64_tr_b16 v[94:95], v109
	ds_read_b64_tr_b16 v[92:93], v108
	v_cvt_pk_bf16_f32 v90, v113, v114
	v_cvt_pk_bf16_f32 v91, v115, v116
	ds_read_b64_tr_b16 v[98:99], v109 offset:32
	ds_read_b64_tr_b16 v[96:97], v108 offset:32
	ds_read_b64_tr_b16 v[100:101], v108 offset:64
	ds_read_b64_tr_b16 v[104:105], v108 offset:96
	ds_read_b64_tr_b16 v[102:103], v109 offset:64
	ds_read_b64_tr_b16 v[106:107], v109 offset:96
	s_waitcnt lgkmcnt(6)
	v_mfma_f32_16x16x32_bf16 v[54:57], v[92:95], v[88:91], v[54:57]
	v_add_f32_e32 v92, v112, v110
	v_add_f32_e32 v92, v113, v92
	v_add_f32_e32 v92, v114, v92
	v_add_f32_e32 v110, v115, v92
	ds_read_b64_tr_b16 v[92:93], v108 offset:128
	ds_read_b64_tr_b16 v[94:95], v109 offset:128
	s_waitcnt lgkmcnt(6)
	v_mfma_f32_16x16x32_bf16 v[58:61], v[96:99], v[88:91], v[58:61]
	v_exp_f32_e32 v111, v87
	s_min_u32 s27, s78, 0x70
	s_min_u32 s30, s78, 0x60
	s_waitcnt lgkmcnt(3)
	v_mfma_f32_16x16x32_bf16 v[62:65], v[100:103], v[88:91], v[62:65]
	s_waitcnt lgkmcnt(2)
	v_mfma_f32_16x16x32_bf16 v[66:69], v[104:107], v[88:91], v[66:69]
	ds_read_b64_tr_b16 v[98:99], v109 offset:160
	ds_read_b64_tr_b16 v[96:97], v108 offset:160
	ds_read_b64_tr_b16 v[100:101], v108 offset:192
	ds_read_b64_tr_b16 v[104:105], v108 offset:224
	ds_read_b64_tr_b16 v[102:103], v109 offset:192
	ds_read_b64_tr_b16 v[106:107], v109 offset:224
	v_exp_f32_e32 v109, v84
	s_waitcnt lgkmcnt(6)
	v_mfma_f32_16x16x32_bf16 v[70:73], v[92:95], v[88:91], v[70:73]
	v_exp_f32_e32 v92, v85
	v_add_f32_e32 v85, v116, v110
	v_add_f32_e32 v85, v111, v85
	v_exp_f32_e32 v110, v86
	v_add_f32_e32 v108, v92, v85
	s_waitcnt lgkmcnt(0)
	v_mfma_f32_16x16x32_bf16 v[84:87], v[104:107], v[88:91], v[50:53]
	s_nop 2
	v_or_b32_e32 v50, s27, v179
	v_mad_u32_u24 v104, v50, s86, v175
	v_add_u32_e32 v50, s30, v183
	v_mad_u32_u24 v105, v50, s86, v175
	ds_read_b64_tr_b16 v[52:53], v105
	ds_read_b64_tr_b16 v[50:51], v104 offset:34816
	v_mfma_f32_16x16x32_bf16 v[74:77], v[96:99], v[88:91], v[74:77]
	v_mfma_f32_16x16x32_bf16 v[78:81], v[100:103], v[88:91], v[78:81]
	v_cvt_pk_bf16_f32 v90, v110, v110
	v_cvt_pk_bf16_f32 v88, v111, v92
	v_cvt_pk_bf16_f32 v89, v83, v109
	v_mov_b32_e32 v91, v90
	ds_read_b64_tr_b16 v[94:95], v105 offset:32
	ds_read_b64_tr_b16 v[92:93], v104 offset:34848
	ds_read_b64_tr_b16 v[96:97], v104 offset:34880
	ds_read_b64_tr_b16 v[100:101], v104 offset:34912
	ds_read_b64_tr_b16 v[98:99], v105 offset:64
	ds_read_b64_tr_b16 v[102:103], v105 offset:96
	s_waitcnt lgkmcnt(6)
	v_mfma_f32_16x16x32_bf16 v[54:57], v[50:53], v[88:91], v[54:57]
	v_add_f32_e32 v50, v83, v108
	v_add_f32_e32 v50, v109, v50
	v_add_f32_e32 v50, v110, v50
	v_add_f32_e32 v50, v110, v50
	v_add_f32_e32 v50, v110, v50
	v_add_f32_e32 v83, v110, v50
	ds_read_b64_tr_b16 v[50:51], v104 offset:34944
	ds_read_b64_tr_b16 v[52:53], v105 offset:128
	ds_bpermute_b32 v106, v184, v83
	s_waitcnt lgkmcnt(1)
	v_mfma_f32_16x16x32_bf16 v[70:73], v[50:53], v[88:91], v[70:73]
	s_waitcnt lgkmcnt(0)
	v_add_f32_e32 v52, v83, v106
	ds_bpermute_b32 v53, v185, v52
	v_lshl_or_b32 v50, s26, 4, v171
	v_mfma_f32_16x16x32_bf16 v[58:61], v[92:95], v[88:91], v[58:61]
	v_mov_b32_e32 v51, s63
	s_ashr_i32 s63, s62, 31
	s_waitcnt lgkmcnt(0)
	v_add_f32_e32 v52, v52, v53
	v_mfma_f32_16x16x32_bf16 v[62:65], v[96:99], v[88:91], v[62:65]
	v_fmac_f32_e32 v52, 0, v110
	v_mad_i32_i24 v156, v50, s61, v51
	s_lshl_b64 s[26:27], s[62:63], 12
	v_mfma_f32_16x16x32_bf16 v[66:69], v[100:103], v[88:91], v[66:69]
	ds_read_b64_tr_b16 v[94:95], v105 offset:160
	ds_read_b64_tr_b16 v[92:93], v104 offset:34976
	ds_read_b64_tr_b16 v[96:97], v104 offset:35008
	ds_read_b64_tr_b16 v[100:101], v104 offset:35040
	ds_read_b64_tr_b16 v[98:99], v105 offset:192
	ds_read_b64_tr_b16 v[102:103], v105 offset:224
	v_lshl_add_u64 v[50:51], s[26:27], 0, v[156:157]
	s_lshl_b64 s[26:27], s[58:59], 24
	s_waitcnt lgkmcnt(4)
	v_mfma_f32_16x16x32_bf16 v[74:77], v[92:95], v[88:91], v[74:77]
	s_add_u32 s26, s28, s26
	s_addc_u32 s27, s29, s27
	s_waitcnt lgkmcnt(1)
	v_mfma_f32_16x16x32_bf16 v[78:81], v[96:99], v[88:91], v[78:81]
	s_waitcnt lgkmcnt(0)
	v_mfma_f32_16x16x32_bf16 v[84:87], v[100:103], v[88:91], v[84:87]
	v_rcp_f32_e32 v88, v52
	v_lshlrev_b64 v[90:91], 11, v[50:51]
	v_lshl_add_u64 v[90:91], s[26:27], 0, v[90:91]
	s_lshl_b32 s26, s60, 8
	v_pk_mul_f32 v[54:55], v[88:89], v[54:55] op_sel_hi:[0,1]
	v_cvt_pk_bf16_f32 v53, v54, v55
	v_pk_mul_f32 v[54:55], v[88:89], v[56:57] op_sel_hi:[0,1]
	v_cvt_pk_bf16_f32 v56, v54, v55
	v_pk_mul_f32 v[54:55], v[88:89], v[58:59] op_sel_hi:[0,1]
	v_cvt_pk_bf16_f32 v83, v54, v55
	v_cndmask_b32_e64 v57, v53, v83, s[4:5]
	v_pk_mul_f32 v[54:55], v[88:89], v[60:61] op_sel_hi:[0,1]
	ds_bpermute_b32 v89, v184, v57
	v_cvt_pk_bf16_f32 v54, v54, v55
	v_cndmask_b32_e64 v55, v56, v54, s[4:5]
	ds_bpermute_b32 v55, v184, v55
	s_mov_b32 s27, s59
	s_waitcnt lgkmcnt(1)
	v_pk_mul_f32 v[60:61], v[88:89], v[62:63] op_sel_hi:[0,1]
	v_cvt_pk_bf16_f32 v62, v60, v61
	v_pk_mul_f32 v[60:61], v[88:89], v[64:65] op_sel_hi:[0,1]
	v_cvt_pk_bf16_f32 v63, v60, v61
	v_pk_mul_f32 v[60:61], v[88:89], v[66:67] op_sel_hi:[0,1]
	v_cvt_pk_bf16_f32 v64, v60, v61
	v_pk_mul_f32 v[60:61], v[88:89], v[68:69] op_sel_hi:[0,1]
	v_cvt_pk_bf16_f32 v60, v60, v61
	s_waitcnt lgkmcnt(0)
	v_cndmask_b32_e64 v57, v54, v55, s[4:5]
	v_cndmask_b32_e64 v54, v63, v60, s[4:5]
	ds_bpermute_b32 v61, v184, v54
	v_cndmask_b32_e64 v54, v62, v64, s[4:5]
	v_lshl_add_u64 v[90:91], v[90:91], 0, s[26:27]
	ds_bpermute_b32 v65, v184, v54
	v_lshl_add_u64 v[58:59], v[90:91], 0, v[162:163]
	v_cndmask_b32_e64 v55, v55, v56, s[4:5]
	v_cndmask_b32_e64 v56, v83, v89, s[4:5]
	v_cndmask_b32_e64 v54, v89, v53, s[4:5]
	global_store_dwordx4 v[58:59], v[54:57], off
	s_waitcnt lgkmcnt(1)
	s_nop 0
	v_cndmask_b32_e64 v57, v60, v61, s[4:5]
	v_cndmask_b32_e64 v55, v61, v63, s[4:5]
	v_pk_mul_f32 v[60:61], v[88:89], v[70:71] op_sel_hi:[0,1]
	v_cvt_pk_bf16_f32 v53, v60, v61
	v_pk_mul_f32 v[60:61], v[88:89], v[72:73] op_sel_hi:[0,1]
	v_cvt_pk_bf16_f32 v63, v60, v61
	v_pk_mul_f32 v[60:61], v[88:89], v[74:75] op_sel_hi:[0,1]
	s_waitcnt lgkmcnt(0)
	v_cndmask_b32_e64 v56, v64, v65, s[4:5]
	v_cvt_pk_bf16_f32 v64, v60, v61
	v_pk_mul_f32 v[60:61], v[88:89], v[76:77] op_sel_hi:[0,1]
	v_cvt_pk_bf16_f32 v60, v60, v61
	v_cndmask_b32_e64 v54, v63, v60, s[4:5]
	ds_bpermute_b32 v61, v184, v54
	v_cndmask_b32_e64 v54, v53, v64, s[4:5]
	ds_bpermute_b32 v66, v184, v54
	v_cndmask_b32_e64 v54, v65, v62, s[4:5]
	global_store_dwordx4 v[58:59], v[54:57], off offset:64
	s_waitcnt lgkmcnt(1)
	s_nop 0
	v_cndmask_b32_e64 v57, v60, v61, s[4:5]
	v_cndmask_b32_e64 v55, v61, v63, s[4:5]
	v_pk_mul_f32 v[60:61], v[88:89], v[78:79] op_sel_hi:[0,1]
	v_cvt_pk_bf16_f32 v62, v60, v61
	v_pk_mul_f32 v[60:61], v[88:89], v[80:81] op_sel_hi:[0,1]
	v_cvt_pk_bf16_f32 v63, v60, v61
	v_pk_mul_f32 v[60:61], v[88:89], v[84:85] op_sel_hi:[0,1]
	s_waitcnt lgkmcnt(0)
	v_cndmask_b32_e64 v56, v64, v66, s[4:5]
	v_cvt_pk_bf16_f32 v64, v60, v61
	v_pk_mul_f32 v[60:61], v[88:89], v[86:87] op_sel_hi:[0,1]
	v_cvt_pk_bf16_f32 v60, v60, v61
	v_cndmask_b32_e64 v54, v63, v60, s[4:5]
	ds_bpermute_b32 v61, v184, v54
	v_cndmask_b32_e64 v54, v62, v64, s[4:5]
	ds_bpermute_b32 v65, v184, v54
	v_cndmask_b32_e64 v54, v66, v53, s[4:5]
	global_store_dwordx4 v[58:59], v[54:57], off offset:128
	s_waitcnt lgkmcnt(1)
	s_nop 0
	v_cndmask_b32_e64 v57, v60, v61, s[4:5]
	v_cndmask_b32_e64 v55, v61, v63, s[4:5]
	s_waitcnt lgkmcnt(0)
	v_cndmask_b32_e64 v56, v64, v65, s[4:5]
	v_cndmask_b32_e64 v54, v65, v62, s[4:5]
	global_store_dwordx4 v[58:59], v[54:57], off offset:192
	s_and_saveexec_b64 s[26:27], s[24:25]
	s_cbranch_execz .LBB0_692
	v_log_f32_e32 v52, v52
	s_lshl_b64 s[30:31], s[58:59], 18
	s_add_u32 s30, s69, s30
	s_addc_u32 s31, s85, s31
	v_lshlrev_b64 v[50:51], 5, v[50:51]
	s_mov_b32 s61, s59
	v_add_f32_e32 v52, v82, v52
	v_lshl_add_u64 v[50:51], s[30:31], 0, v[50:51]
	v_mul_f32_e32 v52, 0x3f317218, v52
	v_lshl_add_u64 v[50:51], s[60:61], 2, v[50:51]
	global_store_dword v[50:51], v52, off
	s_branch .LBB0_692

	.amdhsa_kernel _Z10fwd_kernel4Args
		.amdhsa_group_segment_fixed_size 0
		.amdhsa_private_segment_fixed_size 0
		.amdhsa_kernarg_size 456
		.amdhsa_user_sgpr_count 2
		.amdhsa_user_sgpr_dispatch_ptr 0
		.amdhsa_user_sgpr_queue_ptr 0
		.amdhsa_user_sgpr_kernarg_segment_ptr 1
		.amdhsa_user_sgpr_dispatch_id 0
		.amdhsa_user_sgpr_kernarg_preload_length 0
		.amdhsa_user_sgpr_kernarg_preload_offset 0
		.amdhsa_user_sgpr_private_segment_size 0
		.amdhsa_uses_dynamic_stack 0
		.amdhsa_enable_private_segment 0
		.amdhsa_system_sgpr_workgroup_id_x 1
		.amdhsa_system_sgpr_workgroup_id_y 0
		.amdhsa_system_sgpr_workgroup_id_z 0
		.amdhsa_system_sgpr_workgroup_info 0
		.amdhsa_system_vgpr_workitem_id 0
		.amdhsa_next_free_vgpr 255
		.amdhsa_next_free_sgpr 100
		.amdhsa_accum_offset 256
		.amdhsa_reserve_vcc 1
		.amdhsa_float_round_mode_32 0
		.amdhsa_float_round_mode_16_64 0
		.amdhsa_float_denorm_mode_32 3
		.amdhsa_float_denorm_mode_16_64 3
		.amdhsa_dx10_clamp 1
		.amdhsa_ieee_mode 1
		.amdhsa_fp16_overflow 0
		.amdhsa_tg_split 0
		.amdhsa_exception_fp_ieee_invalid_op 0
		.amdhsa_exception_fp_denorm_src 0
		.amdhsa_exception_fp_ieee_div_zero 0
		.amdhsa_exception_fp_ieee_overflow 0
		.amdhsa_exception_fp_ieee_underflow 0
		.amdhsa_exception_fp_ieee_inexact 0
		.amdhsa_exception_int_div_zero 0
	.end_amdhsa_kernel

amdhsa.kernels:
  - .agpr_count:     0
    .args:
      - .offset:         0
        .size:           200
        .value_kind:     by_value
      - .offset:         200
        .size:           4
        .value_kind:     hidden_block_count_x
      - .offset:         204
        .size:           4
        .value_kind:     hidden_block_count_y
      - .offset:         208
        .size:           4
        .value_kind:     hidden_block_count_z
      - .offset:         212
        .size:           2
        .value_kind:     hidden_group_size_x
      - .offset:         214
        .size:           2
        .value_kind:     hidden_group_size_y
      - .offset:         216
        .size:           2
        .value_kind:     hidden_group_size_z
      - .offset:         218
        .size:           2
        .value_kind:     hidden_remainder_x
      - .offset:         220
        .size:           2
        .value_kind:     hidden_remainder_y
      - .offset:         222
        .size:           2
        .value_kind:     hidden_remainder_z
      - .offset:         240
        .size:           8
        .value_kind:     hidden_global_offset_x
      - .offset:         248
        .size:           8
        .value_kind:     hidden_global_offset_y
      - .offset:         256
        .size:           8
        .value_kind:     hidden_global_offset_z
      - .offset:         264
        .size:           2
        .value_kind:     hidden_grid_dims
      - .offset:         320
        .size:           4
        .value_kind:     hidden_dynamic_lds_size
    .group_segment_fixed_size: 0
    .kernarg_segment_align: 8
    .kernarg_segment_size: 456
    .language:       OpenCL C
    .language_version:
      - 2
      - 0
    .max_flat_workgroup_size: 512
    .name:           _Z10fwd_kernel4Args
    .private_segment_fixed_size: 0
    .sgpr_count:     106
    .sgpr_spill_count: 16
    .symbol:         _Z10fwd_kernel4Args.kd
    .uniform_work_group_size: 1
    .uses_dynamic_stack: false
    .vgpr_count:     255
    .vgpr_spill_count: 0
    .wavefront_size: 64
